# gu/win: tile-scheduler fast path (next tile = same row tile, +4 column tiles when G==256 inside a full group); skips the division block
# speedup vs baseline: 1.0083x; 1.0083x over previous
;     __device__ __forceinline__ bool next(int i, pg8::Unit& u) const { if (!base.next(i >> 2, u)) return false; u.sub = i & 3; return true; }
;     __host__ __device__ bool next(int i, Unit& u) const {
;         const long L = (long)i * G + c; if (L >= nwg) return false;
;         int wgid = (int)L; { const int q = nwg / NXCD, r = nwg % NXCD, xcd = wgid % NXCD, off = wgid / NXCD; wgid = (xcd < r ? xcd * (q + 1) : r * (q + 1) + (xcd - r) * q) + off; }
;         const int nig = WGM * nN, gid = wgid / nig, fm = gid * WGM, gsz = (nM - fm) < WGM ? (nM - fm) : WGM;
;         u.pm = fm + ((wgid % nig) % gsz); u.pn = (wgid % nig) / gsz; u.sub = 0; return true;
; __device__ __forceinline__ void rstd8(const float* ssq, int row0, int fq, float (&rs)[8]) {
;     f32x4 pr[8];
; #pragma unroll
;     for (int i = 0; i < 8; ++i) pr[i] = *(const f32x4*)(ssq + (size_t)(row0 + (i >> 2) * 128 + (i & 3) * 16) * 16 + 4 * fq);
.LBB0_332:
	ds_read_b128 v[150:153], v161
	ds_read_b128 v[172:175], v161 offset:1024
	ds_read_b128 v[176:179], v161 offset:2048
	ds_read_b128 v[180:183], v161 offset:3072
	ds_read_b128 v[184:187], v163
	ds_read_b128 v[192:195], v163 offset:1024
	ds_read_b128 v[196:199], v163 offset:2048
	ds_read_b128 v[200:203], v163 offset:3072
	ds_read_b128 v[204:207], v167
	ds_read_b128 v[208:211], v167 offset:1024
	ds_read_b128 v[212:215], v167 offset:2048
	ds_read_b128 v[216:219], v167 offset:3072
	ds_read_b128 v[220:223], v167 offset:4096
	ds_read_b128 v[224:227], v167 offset:5120
	ds_read_b128 v[228:231], v167 offset:6144
	ds_read_b128 v[232:235], v167 offset:7168
	v_lshl_add_u32 v10, s36, 8, v1
	v_mov_b32_e32 v11, 0
	v_lshlrev_b32_e32 v10, 6, v10
	v_mov_b32_e32 v14, 0x2000
	v_mov_b32_e32 v15, 0
	v_lshl_add_u64 v[12:13], v[140:141], 0, v[10:11]
	v_lshl_add_u64 v[14:15], v[12:13], 0, v[14:15]
	global_load_dwordx4 v[6:9], v[12:13], off
	global_load_dwordx4 v[18:21], v[12:13], off offset:1024
	global_load_dwordx4 v[22:25], v[12:13], off offset:2048
	global_load_dwordx4 v[34:37], v[12:13], off offset:3072
	global_load_dwordx4 v[38:41], v[14:15], off
	global_load_dwordx4 v[50:53], v[14:15], off offset:1024
	global_load_dwordx4 v[54:57], v[14:15], off offset:2048
	global_load_dwordx4 v[58:61], v[14:15], off offset:3072
	s_add_i32 s61, s61, 1
	s_mul_i32 s2, s61, s57
	s_mul_hi_u32 s3, s61, s44
	s_add_i32 s3, s3, s2
	s_mul_i32 s2, s61, s44
	s_add_u32 s30, s2, s25
	s_addc_u32 s31, s3, s45
	v_cmp_gt_i64_e32 vcc, s[30:31], v[148:149]
	v_cmp_lt_i64_e64 s[2:3], s[30:31], v[146:147]
	s_cbranch_vccnz .LBB0_338
	s_cmp_lg_u32 s44, 0x100
	s_cbranch_scc1 .Lsf0
	s_cmp_ge_u32 s36, 0xc0
	s_cbranch_scc1 .Lsf0
	s_add_i32 s26, s37, 4
	s_cmp_ge_u32 s26, 22
	s_cbranch_scc1 .Lsf0
	s_mov_b32 s28, s36
	s_branch .LBB0_338
.Lsf0:
	s_ashr_i32 s15, s30, 31
	s_lshr_b32 s15, s15, 29
	s_add_i32 s15, s30, s15
	s_and_b32 s18, s15, -8
	s_sub_i32 s18, s30, s18
	s_cmp_gt_i32 s18, 3
	s_mov_b64 s[26:27], -1
	s_cbranch_scc0 .LBB0_335
	s_mul_i32 s19, s18, 0x215
	s_add_i32 s19, s19, 4
	s_mov_b64 s[26:27], 0

; #define PG8_STAGE(bufoff, gbase, voff) do { _Pragma("unroll") for (int _i = 0; _i < 2; ++_i) \
;         __builtin_amdgcn_global_load_lds((const unsigned*)((const char*)(gbase) + (voff)[_i]), (PG8_LAS unsigned*)(lds + (bufoff) + ldsw + _i * 8192), 16, 0, 0); } while (0)
; #define PG8_LDA(dst, b, h) do { _Pragma("unroll") for (int m = 0; m < 4; ++m) _Pragma("unroll") for (int k = 0; k < 2; ++k) dst[m][k] = *(const PG8_LAS bf16x8*)(lds + PG8_SA(b, h) + aoff + m * 2048 + k * 1024); } while (0)
; #define PG8_LDB(dst, b, h) do { _Pragma("unroll") for (int n = 0; n < 2; ++n) _Pragma("unroll") for (int k = 0; k < 2; ++k) dst[n][k] = *(const PG8_LAS bf16x8*)(lds + PG8_SB(b, h) + boff + n * 2048 + k * 1024); } while (0)
; #define PG8_SCHED __builtin_amdgcn_sched_barrier(0)
;     __device__ __forceinline__ bool next(int i, pg8::Unit& u) const { if (!base.next(i >> 2, u)) return false; u.sub = i & 3; return true; }
;     __host__ __device__ bool next(int i, Unit& u) const {
;         const long L = (long)i * G + c; if (L >= nwg) return false;
;         int wgid = (int)L; { const int q = nwg / NXCD, r = nwg % NXCD, xcd = wgid % NXCD, off = wgid / NXCD; wgid = (xcd < r ? xcd * (q + 1) : r * (q + 1) + (xcd - r) * q) + off; }
;         const int nig = WGM * nN, gid = wgid / nig, fm = gid * WGM, gsz = (nM - fm) < WGM ? (nM - fm) : WGM;
;         u.pm = fm + ((wgid % nig) % gsz); u.pn = (wgid % nig) / gsz; u.sub = 0; return true;
; template <class Epi, class Sched, bool ALIGN_EPI = false, bool SP2 = false>
; __device__ __forceinline__ void gemm_phase(PG8_LAS unsigned char* lds, const Gemm g, const Sched& S, const Epi& E, const int tid) {
;     ...
;             PG8_LDB(B0, 0, 0); PG8_LDB(B1, 0, 1); PG8_SCHED; PG8_LDA(At, 0, 0); PG8_STAGE(PG8_SA(1, 1), a1 + hstep, voffA);
.LBB0_726:
	ds_read_b128 v[130:133], v191
	ds_read_b128 v[134:137], v191 offset:1024
	ds_read_b128 v[138:141], v191 offset:2048
	ds_read_b128 v[142:145], v191 offset:3072
	ds_read_b128 v[146:149], v193
	ds_read_b128 v[150:153], v193 offset:1024
	ds_read_b128 v[154:157], v193 offset:2048
	ds_read_b128 v[158:161], v193 offset:3072
	ds_read_b128 v[186:189], v197
	ds_read_b128 v[198:201], v197 offset:1024
	ds_read_b128 v[206:209], v197 offset:2048
	ds_read_b128 v[212:215], v197 offset:3072
	ds_read_b128 v[216:219], v197 offset:4096
	ds_read_b128 v[220:223], v197 offset:5120
	ds_read_b128 v[224:227], v197 offset:6144
	ds_read_b128 v[228:231], v197 offset:7168
	s_add_i32 s78, s78, 1
	s_mul_i32 s2, s78, s64
	s_mul_hi_u32 s3, s78, s45
	s_add_i32 s3, s3, s2
	s_mul_i32 s2, s78, s45
	s_add_u32 s30, s2, s44
	s_addc_u32 s31, s3, s65
	v_cmp_gt_i64_e32 vcc, s[30:31], v[184:185]
	v_cmp_lt_i64_e64 s[2:3], s[30:31], v[182:183]
	s_cbranch_vccnz .LBB0_732
	s_cmp_lg_u32 s45, 0x100
	s_cbranch_scc1 .Lsf1
	s_cmp_ge_u32 s4, 0xc0
	s_cbranch_scc1 .Lsf1
	s_add_i32 s26, s36, 4
	s_cmp_ge_u32 s26, 18
	s_cbranch_scc1 .Lsf1
	s_mov_b32 s28, s4
	s_branch .LBB0_732
.Lsf1:
	s_ashr_i32 s15, s30, 31
	s_lshr_b32 s15, s15, 29
	s_add_i32 s15, s30, s15
	s_and_b32 s18, s15, -8
	s_sub_i32 s18, s30, s18
	s_cmp_gt_i32 s18, 3
	s_mov_b64 s[26:27], -1
	s_cbranch_scc0 .LBB0_729
	s_mul_i32 s19, s18, 0x1b4
	s_add_i32 s19, s19, 4
	s_mov_b64 s[26:27], 0
